# GEMM phase prologue: tile-1 LDS-DMA loads issued before the first counted wait (barrier structure kept)
# baseline (speedup 1.0000x reference)
; #define PG8_WAIT_V(n) asm volatile("s_waitcnt vmcnt(" #n ")" ::: "memory")
; #define PG8_BAR __builtin_amdgcn_s_barrier()
; #define PG8_STA(bufoff, gbase, ld) PG8_STAGE(bufoff, gbase, RA0 * (unsigned)(ld) + CC0, RA1 * (unsigned)(ld) + CC1)
; #define PG8_STB(bufoff, gbase, ld) PG8_STAGE(bufoff, gbase, RB0 * (unsigned)(ld) + CC0, RB1 * (unsigned)(ld) + CC1)
; __device__ __forceinline__ void epi_rstd(const float* ssq, int row0, int fq, float (&rs)[2][4]) {
;     ...
;             for (int j = 0; j < 4; ++j) part[ai][m][j] = ssq[(size_t)(4 * fq + j) * M + row0 + ai * 128 + m * 16];
; #pragma unroll
;     for (int ai = 0; ai < 2; ++ai)
; #pragma unroll
;         for (int m = 0; m < 4; ++m) { float t = (part[ai][m][0] + part[ai][m][1]) + (part[ai][m][2] + part[ai][m][3]); t += __shfl_xor(t, 16); t += __shfl_xor(t, 32); rs[ai][m] = __builtin_amdgcn_rsqf(t * (1.0f / 1024.0f) + EPS); }
; __device__ __forceinline__ void gemm_phase(LAS unsigned char* lds, const Sched& S, const Epi& E) {
;     ...
;     PG8_WAIT_V(2); PG8_BAR;
;     PG8_STB(PG8_SB(1, 0), cB + kstep, ldb); PG8_STA(PG8_SA(1, 0), cA + kstep, lda); PG8_STB(PG8_SB(1, 1), cB + hB + kstep, ldb);
;     PG8_WAIT_V(6); PG8_BAR; }
.Lmy_tab_done:
	v_bfe_u32 v19, v17, 4, 2
	v_and_b32_e32 v18, 15, v17
	v_lshlrev_b32_e32 v21, 4, v19
	v_lshlrev_b32_e32 v17, 2, v17
	s_and_b32 s11, s7, 3
	v_lshl_or_b32 v239, s6, 6, v18
	v_lshl_or_b32 v18, v18, 6, v21
	s_lshl_b32 s6, s6, 13
	v_and_b32_e32 v17, 32, v17
	v_bitop3_b32 v240, v18, s6, v17 bitop3:0xde
	s_lshl_b32 s6, s11, 12
	v_bitop3_b32 v241, v18, s6, v17 bitop3:0xde
	v_readlane_b32 s6, v250, 7
	v_readlane_b32 s7, v250, 8
	s_lshl_b64 s[6:7], s[6:7], 2
	s_waitcnt lgkmcnt(0)
	s_add_u32 s4, s4, s6
	s_addc_u32 s5, s5, s7
	s_add_u32 s62, s70, 0x800000
	s_addc_u32 s63, s71, 0
	v_lshl_add_u64 v[2:3], v[2:3], 0, s[52:53]
	s_add_i32 m0, s34, 0x18000
	s_nop 0
	global_load_lds_dwordx4 v[2:3], off
	v_lshl_add_u64 v[2:3], v[4:5], 0, s[52:53]
	s_add_i32 m0, s34, 0x1a000
	s_add_i32 s90, s34, 0x8000
	global_load_lds_dwordx4 v[2:3], off
	v_lshl_add_u64 v[2:3], v[10:11], 0, s[52:53]
	s_mov_b32 m0, s90
	s_add_i32 s73, s34, 0xa000
	global_load_lds_dwordx4 v[2:3], off
	v_lshl_add_u64 v[2:3], v[12:13], 0, s[52:53]
	s_mov_b32 m0, s73
	v_writelane_b32 v250, s4, 27
	global_load_lds_dwordx4 v[2:3], off
	v_lshl_add_u64 v[2:3], v[6:7], 0, s[52:53]
	s_add_i32 m0, s34, 0x1c000
	v_writelane_b32 v250, s5, 28
	global_load_lds_dwordx4 v[2:3], off
	v_lshl_add_u64 v[2:3], v[8:9], 0, s[52:53]
	s_add_i32 m0, s34, 0x1e000
	global_load_lds_dwordx4 v[2:3], off
	v_readlane_b32 s12, v250, 41
	s_nop 0
	s_cmp_eq_u32 s12, -1
	s_cbranch_scc1 .Lmy_w2
	s_waitcnt vmcnt(24)
	s_branch .Lmy_wdone
.Lmy_w2:
	s_waitcnt vmcnt(8)
.Lmy_wdone:
	s_barrier
	s_cmpk_lt_u32 s2, 0x100
	s_cselect_b64 s[4:5], -1, 0
	s_lshl_b32 s6, s11, 14
	v_writelane_b32 v250, s11, 29
	s_or_b32 s6, s6, 0xfff80000
	v_writelane_b32 v250, s6, 30
	s_lshl_b32 s82, s15, 3
	v_readlane_b32 s6, v250, 21
	v_readlane_b32 s7, v250, 22
	v_readlane_b32 s61, v250, 20
	s_waitcnt vmcnt(6)
	v_readlane_b32 s12, v250, 41
	s_nop 0
	s_cmp_eq_u32 s12, -1
	s_cbranch_scc1 .Lmy_red_skip
	v_add_f32_e32 v66, v66, v67
	v_add_f32_e32 v68, v68, v69
	v_add_f32_e32 v66, v66, v68
	v_add_f32_e32 v70, v70, v71
	v_add_f32_e32 v72, v72, v73
	v_add_f32_e32 v70, v70, v72
	v_add_f32_e32 v74, v74, v75
	v_add_f32_e32 v76, v76, v77
	v_add_f32_e32 v74, v74, v76
	v_add_f32_e32 v78, v78, v79
	v_add_f32_e32 v80, v80, v81
	v_add_f32_e32 v78, v78, v80
	v_add_f32_e32 v66, v66, v70
	v_add_f32_e32 v74, v74, v78
	v_add_f32_e32 v66, v66, v74
	v_fmamk_f32 v66, v66, 0x3a800000, v197
	v_rsq_f32_e32 v66, v66
	v_and_b32_e32 v65, 0xff, v195
	v_lshlrev_b32_e32 v65, 2, v65
	v_add_u32_e32 v65, 0x20800, v65
	ds_write_b32 v65, v66
	v_writelane_b32 v250, s95, 41
